# v99 + MLA attention unit index remapped so each XCD streams two heads at a time (16 CUs per K/V tile)
# speedup vs baseline: 1.0003x; 1.0003x over previous
; #define LAS __attribute__((address_space(3)))
; #define GAS __attribute__((address_space(1)))
; #define ATT_LOADK(kt) do { const int k0_ = ATT_KEY0(kt); \
;         _Pragma("unroll") for (int p = 0; p < KPT; ++p) { const int c = tid + 512 * p; if (c < KCH) kr[p] = *(const GAS u32x4*)((const GAS char*)(Kb + (size_t)k0_ * DQK) + (unsigned)(c * 16)); } } while (0)
; template <int DQK, int DV, int NAT, int VSHIFT, int COMB> ...
;     ...
;         if (ui < NBIG) { bx_ = ui >> 5; qb = 1 + (ui & 31); } else { bx_ = ui - NBIG; qb = 0; }
; #pragma unroll 1
;       for (int s2 = 0; s2 < (COMB ? 2 : 1); ++s2) {
;         const int bv = COMB ? ((bx_ >> 3) * 16 + (bx_ & 7) * 2 + s2) : bx_;
;         const int b = bv >> 4, vh = bv & 15, hv = vh >> VSHIFT;
;         const bf16_t* Kb = K + (size_t)bv * TPB * DQK;
;         const bf16_t* Vb = Vt + (size_t)hv * DV * MTOT + (size_t)b * TPB;
;         int nkt, lo = 0;
;         if (qb == 0) nkt = 4;
;         else if (!NAT) nkt = TPB / 64;
;         else { const int r0 = (qb - 1) * 4; lo = min(max(r0 - 4, 0), 120); const int hi = min(max(r0 - 1, 0), 120) + 8; nkt = 4 + hi - lo; }
;         const int pos_q = qb * 256 + w * 32 + n;
;         const int qr = (qb - 1) * 4 + (w >> 1), qrs = min(max(qr - 4, 0), 120);
;         int lq_ = lane; asm volatile("" : "+v"(lq_));
;         const bf16_t* qp = Q + ((size_t)bv * TPB + qb * 256 + w * 32 + (lq_ & 31)) * DQK + (lq_ >> 5) * 8;
;         bf16x8 qg[DQK / 16];
; #pragma unroll
;         for (int ks = 0; ks < DQK / 16; ++ks) qg[ks] = *(const GAS bf16x8*)(qp + ks * 16);
;     ...
;         __syncthreads();
;         if (NAT) { for (int i = tid; i < 465; i += 512) rpb_s[i] = rpb[vh * 465 + i]; }
; #pragma unroll
;         for (int ks = 0; ks < DQK / 16; ++ks) { if (!QREG) *(LAS bf16x8*)(qs + ks * 1024) = qg[ks]; }
;         if (K128) { ATT_DMAK(0, 0); ATT_DMAV(0, 0); ATT_DMAK(1, 1); ATT_DMAV(1, 1); ATT_DMAK(2, 2); asm volatile("s_waitcnt vmcnt(0)" ::: "memory"); }
;         else if (DMA) { ATT_DMAK(0, 0); ATT_DMAV(0, 0); ATT_DMAK(1, 1); asm volatile("s_waitcnt vmcnt(0)" ::: "memory"); }
;         else { ATT_LOADK(0); ATT_STOREK(0); ATT_LOADV(0); ATT_STOREV(0); ATT_LOADK(1); ATT_STOREK(1); }
;         __syncthreads();
;         f32x16 sA0, sA1, sB0, sB1;
;         ATT_QK(sA0, sA1, 0);
;         __syncthreads();
.LBB0_501:
	s_bfe_u32 s0, s28, 0x50001
	s_lshl_b32 s0, s0, 8
	s_cmpk_gt_i32 s28, 0x7ff
	s_cselect_b32 s34, 4, 0x84
	s_addk_i32 s0, 0x100
	s_cmpk_gt_i32 s28, 0x7ff
	s_cselect_b32 s29, 0, s0
	s_lshr_b32 s0, s28, 6
	s_lshl_b32 s0, s0, 1
	s_and_b32 s1, s28, 1
	s_or_b32 s0, s0, s1
	s_add_i32 s1, s28, 0xfffff800
	s_cmpk_gt_i32 s28, 0x7ff
	s_cselect_b32 s37, s1, s0
	s_and_b32 s30, s37, 15
	s_ashr_i32 s31, s37, 4
	s_mul_i32 s0, s30, 0x420000
	v_readlane_b32 s11, v253, 53
	s_add_u32 s0, s11, s0
	v_readlane_b32 s11, v253, 54
	s_mul_i32 s10, s31, 0x4200
	s_addc_u32 s11, s11, 0
	s_mul_hi_i32 s1, s31, 0x4200
	s_add_u32 s0, s0, s10
	s_mul_i32 s5, s37, 0x2100
	s_addc_u32 s1, s11, s1
	s_mul_hi_i32 s4, s37, 0x2100
	v_lshl_add_u64 v[2:3], s[0:1], 0, v[164:165]
	v_mov_b32_e32 v0, v173
	s_add_u32 s0, s29, s5
	v_mov_b32_e32 v7, s25
	v_and_or_b32 v6, v0, 31, s24
	s_addc_u32 s1, 0, s4
	v_lshl_add_u64 v[6:7], s[0:1], 0, v[6:7]
	v_readlane_b32 s0, v253, 40
	v_readlane_b32 s1, v253, 41
	s_movk_i32 s4, 0xc0
	s_mul_i32 s9, s37, 0x18c000
	v_mov_b64_e32 v[8:9], s[0:1]
	v_mad_u64_u32 v[8:9], s[0:1], v6, s4, v[8:9]
	v_readlane_b32 s0, v253, 42
	s_mul_hi_i32 s8, s37, 0x18c000
	v_ashrrev_i32_e32 v0, 2, v0
	v_readlane_b32 s1, v253, 43
	s_add_u32 s0, s0, s9
	v_and_b32_e32 v6, -8, v0
	s_addc_u32 s1, s1, s8
	v_mad_i32_i24 v9, v7, s4, v9
	v_ashrrev_i32_e32 v7, 31, v6
	s_add_u32 s4, s0, 0x6000
	v_lshl_add_u64 v[6:7], v[6:7], 1, v[8:9]
	s_addc_u32 s5, s1, 0
	s_mov_b32 m0, s26
	global_load_dwordx4 v[114:117], v[6:7], off
	global_load_dwordx4 v[118:121], v[6:7], off offset:32
	global_load_dwordx4 v[122:125], v[6:7], off offset:64
	global_load_dwordx4 v[126:129], v[6:7], off offset:96
	global_load_dwordx4 v[130:133], v[6:7], off offset:128
	global_load_dwordx4 v[134:137], v[6:7], off offset:160
	s_add_u32 s8, s0, 0x3000
	v_lshl_add_u64 v[6:7], s[0:1], 0, v[160:161]
	s_addc_u32 s9, s1, 0
	s_waitcnt vmcnt(0)
	s_barrier
	global_load_lds_dwordx4 v[6:7], off
	v_lshl_add_u64 v[6:7], s[0:1], 0, v[162:163]
	s_add_i32 m0, s26, 0x2000
	v_lshl_add_u64 v[4:5], v[2:3], 0, s[74:75]
	global_load_lds_dwordx4 v[6:7], off
	s_add_i32 m0, s26, 0x10000
	v_add_u32_e32 v0, v159, v184
	global_load_lds_dwordx4 v[2:3], off
	v_lshl_add_u64 v[2:3], s[8:9], 0, v[160:161]
	s_add_i32 m0, s26, 0x4000
	s_mov_b32 s36, 2
	global_load_lds_dwordx4 v[2:3], off
	v_lshl_add_u64 v[2:3], s[8:9], 0, v[162:163]
	s_add_i32 m0, s26, 0x6000
	s_mov_b32 s8, 0
	global_load_lds_dwordx4 v[2:3], off
	s_add_i32 m0, s26, 0x12000
	v_lshl_add_u64 v[2:3], s[4:5], 0, v[160:161]
	global_load_lds_dwordx4 v[4:5], off
	s_add_i32 m0, s26, 0x8000
	s_movk_i32 s35, 0x4000
	global_load_lds_dwordx4 v[2:3], off
	v_lshl_add_u64 v[2:3], s[4:5], 0, v[162:163]
	s_add_i32 m0, s26, 0xa000
	s_nop 0
	global_load_lds_dwordx4 v[2:3], off
	s_waitcnt vmcnt(0)
	s_waitcnt vmcnt(0) lgkmcnt(0)
	s_barrier
	ds_read_b128 v[2:5], v0
	ds_read_b128 v[6:9], v0 offset:8192
	v_add_u32_e32 v0, v159, v185
	ds_read_b128 v[10:13], v0
	ds_read_b128 v[14:17], v0 offset:8192
	v_add_u32_e32 v0, v159, v186
	ds_read_b128 v[18:21], v0
	ds_read_b128 v[22:25], v0 offset:8192
	v_add_u32_e32 v0, v159, v187
	ds_read_b128 v[26:29], v0
	ds_read_b128 v[30:33], v0 offset:8192
	v_add_u32_e32 v0, v159, v188
	ds_read_b128 v[34:37], v0
	ds_read_b128 v[38:41], v0 offset:8192
	v_add_u32_e32 v0, v159, v189
	ds_read_b128 v[42:45], v0
	ds_read_b128 v[82:85], v0 offset:8192
	s_waitcnt lgkmcnt(11)
	v_mfma_f32_32x32x16_bf16 v[66:81], v[2:5], v[114:117], 0
	s_mov_b32 s22, s8
	s_mov_b32 s23, s8
	s_mov_b32 s9, s8
	s_mov_b32 s10, s8
	s_mov_b32 s11, s8
	s_mov_b32 s12, s8
	s_mov_b32 s13, s8
	s_waitcnt lgkmcnt(10)
	v_mfma_f32_32x32x16_bf16 v[50:65], v[6:9], v[114:117], 0
	s_mov_b32 s14, s8
	s_mov_b32 s15, s8
	s_mov_b32 s16, s8
	s_mov_b32 s17, s8
	s_mov_b32 s18, s8
	s_mov_b32 s19, s8
	s_mov_b32 s20, s8
	s_waitcnt lgkmcnt(9)
	v_mfma_f32_32x32x16_bf16 v[66:81], v[10:13], v[118:121], v[66:81]
	s_mov_b32 s21, s8
	s_waitcnt lgkmcnt(8)
	v_mfma_f32_32x32x16_bf16 v[50:65], v[14:17], v[118:121], v[50:65]
	s_waitcnt lgkmcnt(7)
	v_mfma_f32_32x32x16_bf16 v[66:81], v[18:21], v[122:125], v[66:81]
	s_waitcnt lgkmcnt(6)
	v_mfma_f32_32x32x16_bf16 v[50:65], v[22:25], v[122:125], v[50:65]
	s_waitcnt lgkmcnt(5)
	v_mfma_f32_32x32x16_bf16 v[66:81], v[26:29], v[126:129], v[66:81]
	s_waitcnt lgkmcnt(4)
	v_mfma_f32_32x32x16_bf16 v[50:65], v[30:33], v[126:129], v[50:65]
	s_waitcnt lgkmcnt(3)
	v_mfma_f32_32x32x16_bf16 v[66:81], v[34:37], v[130:133], v[66:81]
	s_waitcnt lgkmcnt(2)
	v_mfma_f32_32x32x16_bf16 v[50:65], v[38:41], v[130:133], v[50:65]
	s_waitcnt lgkmcnt(1)
	v_mfma_f32_32x32x16_bf16 v[66:81], v[42:45], v[134:137], v[66:81]
	v_mov_b64_e32 v[48:49], s[22:23]
	v_mov_b64_e32 v[46:47], s[20:21]
	v_mov_b64_e32 v[44:45], s[18:19]
	v_mov_b64_e32 v[42:43], s[16:17]
	v_mov_b64_e32 v[40:41], s[14:15]
	v_mov_b64_e32 v[38:39], s[12:13]
	v_mov_b64_e32 v[36:37], s[10:11]
	s_waitcnt lgkmcnt(0)
	v_mfma_f32_32x32x16_bf16 v[50:65], v[82:85], v[134:137], v[50:65]
	v_mov_b64_e32 v[34:35], s[8:9]
	s_mov_b64 s[18:19], 0xb50c000
	s_mov_b64 s[16:17], 0xb509000
	s_mov_b64 s[14:15], 0x6000
	v_mov_b32_e32 v0, 0x420000
	v_mad_u64_u32 v[2:3], s[0:1], s30, v0, v[166:167]
	v_mad_i64_i32 v[176:177], s[0:1], s31, v203, v[2:3]
	v_mov_b32_e32 v2, v1
	v_mov_b32_e32 v3, v1
	v_mov_b32_e32 v4, v1
	v_mov_b32_e32 v5, v1
	v_mov_b32_e32 v6, v1
	v_mov_b32_e32 v7, v1
	v_mov_b32_e32 v8, v1
	v_mov_b32_e32 v9, v1
	v_mov_b32_e32 v10, v1
	v_mov_b32_e32 v11, v1
	v_mov_b32_e32 v12, v1
	v_mov_b32_e32 v13, v1
	v_mov_b32_e32 v14, v1
	v_mov_b32_e32 v15, v1
	v_mov_b32_e32 v16, v1
	v_mov_b32_e32 v17, v1
	v_mov_b32_e32 v18, v1
	v_mov_b32_e32 v19, v1
	v_mov_b32_e32 v20, v1
	v_mov_b32_e32 v21, v1
	v_mov_b32_e32 v22, v1
	v_mov_b32_e32 v23, v1
	v_mov_b32_e32 v24, v1
	v_mov_b32_e32 v25, v1
	v_mov_b32_e32 v26, v1
	v_mov_b32_e32 v27, v1
	v_mov_b32_e32 v28, v1
	v_mov_b32_e32 v29, v1
	v_mov_b32_e32 v30, v1
	v_mov_b32_e32 v31, v1
	v_mov_b32_e32 v0, v1
	v_mov_b64_e32 v[32:33], v[30:31]
	v_mad_i64_i32 v[178:179], s[0:1], s37, v204, v[168:169]
	v_mad_i64_i32 v[180:181], s[0:1], s37, v204, v[174:175]
	v_mov_b32_e32 v183, 0
	v_mov_b64_e32 v[30:31], v[28:29]
	v_mov_b64_e32 v[28:29], v[26:27]
	v_mov_b64_e32 v[26:27], v[24:25]
	v_mov_b64_e32 v[24:25], v[22:23]
	v_mov_b64_e32 v[22:23], v[20:21]
	v_mov_b64_e32 v[20:21], v[18:19]
	v_mov_b64_e32 v[18:19], v[16:17]
	v_mov_b64_e32 v[16:17], v[14:15]
	v_mov_b64_e32 v[14:15], v[12:13]
	v_mov_b64_e32 v[12:13], v[10:11]
	v_mov_b64_e32 v[10:11], v[8:9]
	v_mov_b64_e32 v[8:9], v[6:7]
	v_mov_b64_e32 v[6:7], v[4:5]
	v_mov_b64_e32 v[4:5], v[2:3]
	v_mov_b64_e32 v[2:3], v[0:1]
	s_barrier
	v_readlane_b32 s0, v252, 7
	s_cmpk_lt_u32 s0, 0x100
	s_cbranch_scc0 .Lmpre_skip
	s_mov_b64 s[4:5], -1
	s_mov_b64 s[10:11], 0
